# diff-attn diagonal tile mask rewritten: only one 32-key block is triangular (loop-invariant per-lane pattern, inline-constant compares, 3 rotating mask registers, no s_nop), the other block is kept or
# speedup vs baseline: 1.0016x; 1.0016x over previous
.LBB0_36:
	s_add_i32 s23, s10, -1
	s_and_b32 s23, s23, 1
	s_sub_i32 s26, s22, 63
	s_cmp_gt_u32 s26, s5
	s_cbranch_scc1 .LBB0_43
	s_mul_i32 s26, s23, 0x7400
	s_add_i32 s26, s26, 0
	s_cmp_le_u32 s22, s1
	v_add3_u32 v190, s26, v165, v172
	ds_read_b128 v[98:101], v190
	ds_read_b128 v[102:105], v190 offset:32
	ds_read_b128 v[106:109], v190 offset:64
	ds_read_b128 v[110:113], v190 offset:96
	ds_read_b128 v[240:243], v190 offset:4608
	ds_read_b128 v[244:247], v190 offset:4640
	ds_read_b128 v[214:217], v190 offset:4672
	ds_read_b128 v[190:193], v190 offset:4704
	s_setprio 1
	s_waitcnt lgkmcnt(7)
	v_mfma_f32_32x32x16_bf16 v[82:97], v[98:101], v[126:129], 0
	s_waitcnt lgkmcnt(6)
	v_mfma_f32_32x32x16_bf16 v[82:97], v[102:105], v[130:133], v[82:97]
	s_waitcnt lgkmcnt(5)
	v_mfma_f32_32x32x16_bf16 v[82:97], v[106:109], v[134:137], v[82:97]
	s_waitcnt lgkmcnt(4)
	v_mfma_f32_32x32x16_bf16 v[82:97], v[110:113], v[138:141], v[82:97]
	s_waitcnt lgkmcnt(3)
	v_mfma_f32_32x32x16_bf16 v[98:113], v[240:243], v[126:129], 0
	s_waitcnt lgkmcnt(2)
	v_mfma_f32_32x32x16_bf16 v[98:113], v[244:247], v[130:133], v[98:113]
	s_waitcnt lgkmcnt(1)
	v_mfma_f32_32x32x16_bf16 v[98:113], v[214:217], v[134:137], v[98:113]
	s_waitcnt lgkmcnt(0)
	v_mfma_f32_32x32x16_bf16 v[98:113], v[190:193], v[138:141], v[98:113]
	s_setprio 0
	s_cbranch_scc1 .LBB0_39
	v_mbcnt_lo_u32_b32 v240, -1, 0
	v_mbcnt_hi_u32_b32 v240, -1, v240
	v_lshrrev_b32_e32 v241, 5, v240
	v_and_b32_e32 v240, 31, v240
	v_lshlrev_b32_e32 v241, 2, v241
	v_sub_u32_e32 v240, v240, v241
	s_sub_u32 s78, s22, s1
	s_cmp_eq_u32 s78, 63
	s_cbranch_scc1 .Lda_mE_c1
	v_cmp_gt_i32_e64 vcc, 0, v240
	v_cmp_gt_i32_e64 s[78:79], 1, v240
	v_cmp_gt_i32_e64 s[62:63], 2, v240
	v_cndmask_b32_e64 v98, v98, v220, vcc
	v_cndmask_b32_e64 v99, v99, v220, s[78:79]
	v_cndmask_b32_e64 v100, v100, v220, s[62:63]
	v_cmp_gt_i32_e64 vcc, 3, v240
	v_cmp_gt_i32_e64 s[78:79], 8, v240
	v_cmp_gt_i32_e64 s[62:63], 9, v240
	v_cndmask_b32_e64 v101, v101, v220, vcc
	v_cndmask_b32_e64 v102, v102, v220, s[78:79]
	v_cndmask_b32_e64 v103, v103, v220, s[62:63]
	v_cmp_gt_i32_e64 vcc, 10, v240
	v_cmp_gt_i32_e64 s[78:79], 11, v240
	v_cmp_gt_i32_e64 s[62:63], 16, v240
	v_cndmask_b32_e64 v104, v104, v220, vcc
	v_cndmask_b32_e64 v105, v105, v220, s[78:79]
	v_cndmask_b32_e64 v106, v106, v220, s[62:63]
	v_cmp_gt_i32_e64 vcc, 17, v240
	v_cmp_gt_i32_e64 s[78:79], 18, v240
	v_cmp_gt_i32_e64 s[62:63], 19, v240
	v_cndmask_b32_e64 v107, v107, v220, vcc
	v_cndmask_b32_e64 v108, v108, v220, s[78:79]
	v_cndmask_b32_e64 v109, v109, v220, s[62:63]
	v_cmp_gt_i32_e64 vcc, 24, v240
	v_cmp_gt_i32_e64 s[78:79], 25, v240
	v_cmp_gt_i32_e64 s[62:63], 26, v240
	v_cndmask_b32_e64 v110, v110, v220, vcc
	v_cndmask_b32_e64 v111, v111, v220, s[78:79]
	v_cndmask_b32_e64 v112, v112, v220, s[62:63]
	v_cmp_gt_i32_e64 vcc, 27, v240
	s_nop 1
	v_cndmask_b32_e64 v113, v113, v220, vcc
	s_branch .LBB0_39
.Lda_mE_c1:
	v_cmp_gt_i32_e64 vcc, 0, v240
	v_cmp_gt_i32_e64 s[78:79], 1, v240
	v_cmp_gt_i32_e64 s[62:63], 2, v240
	v_cndmask_b32_e64 v82, v82, v220, vcc
	v_cndmask_b32_e64 v83, v83, v220, s[78:79]
	v_cndmask_b32_e64 v84, v84, v220, s[62:63]
	v_cmp_gt_i32_e64 vcc, 3, v240
	v_cmp_gt_i32_e64 s[78:79], 8, v240
	v_cmp_gt_i32_e64 s[62:63], 9, v240
	v_cndmask_b32_e64 v85, v85, v220, vcc
	v_cndmask_b32_e64 v86, v86, v220, s[78:79]
	v_cndmask_b32_e64 v87, v87, v220, s[62:63]
	v_cmp_gt_i32_e64 vcc, 10, v240
	v_cmp_gt_i32_e64 s[78:79], 11, v240
	v_cmp_gt_i32_e64 s[62:63], 16, v240
	v_cndmask_b32_e64 v88, v88, v220, vcc
	v_cndmask_b32_e64 v89, v89, v220, s[78:79]
	v_cndmask_b32_e64 v90, v90, v220, s[62:63]
	v_cmp_gt_i32_e64 vcc, 17, v240
	v_cmp_gt_i32_e64 s[78:79], 18, v240
	v_cmp_gt_i32_e64 s[62:63], 19, v240
	v_cndmask_b32_e64 v91, v91, v220, vcc
	v_cndmask_b32_e64 v92, v92, v220, s[78:79]
	v_cndmask_b32_e64 v93, v93, v220, s[62:63]
	v_cmp_gt_i32_e64 vcc, 24, v240
	v_cmp_gt_i32_e64 s[78:79], 25, v240
	v_cmp_gt_i32_e64 s[62:63], 26, v240
	v_cndmask_b32_e64 v94, v94, v220, vcc
	v_cndmask_b32_e64 v95, v95, v220, s[78:79]
	v_cndmask_b32_e64 v96, v96, v220, s[62:63]
	v_cmp_gt_i32_e64 vcc, 27, v240
	s_nop 1
	v_cndmask_b32_e64 v97, v97, v220, vcc
	v_mov_b32_e32 v98, v220
	v_mov_b32_e32 v99, v220
	v_mov_b32_e32 v100, v220
	v_mov_b32_e32 v101, v220
	v_mov_b32_e32 v102, v220
	v_mov_b32_e32 v103, v220
	v_mov_b32_e32 v104, v220
	v_mov_b32_e32 v105, v220
	v_mov_b32_e32 v106, v220
	v_mov_b32_e32 v107, v220
	v_mov_b32_e32 v108, v220
	v_mov_b32_e32 v109, v220
	v_mov_b32_e32 v110, v220
	v_mov_b32_e32 v111, v220
	v_mov_b32_e32 v112, v220
	v_mov_b32_e32 v113, v220

.LBB0_51:
	s_add_i32 s23, s22, -1
	s_and_b32 s23, s23, 1
	s_sub_i32 s26, s10, 63
	s_cmp_gt_u32 s26, s5
	s_cbranch_scc1 .LBB0_58
	s_mul_i32 s26, s23, 0x7400
	s_add_i32 s26, s26, 0
	s_cmp_le_u32 s10, s1
	v_add3_u32 v152, s26, v165, v172
	ds_read_b128 v[98:101], v152
	ds_read_b128 v[102:105], v152 offset:32
	ds_read_b128 v[106:109], v152 offset:64
	ds_read_b128 v[110:113], v152 offset:96
	ds_read_b128 v[154:157], v152 offset:4608
	ds_read_b128 v[190:193], v152 offset:4640
	ds_read_b128 v[214:217], v152 offset:4672
	ds_read_b128 v[234:237], v152 offset:4704
	s_setprio 1
	s_waitcnt lgkmcnt(7)
	v_mfma_f32_32x32x16_bf16 v[82:97], v[98:101], v[114:117], 0
	s_waitcnt lgkmcnt(6)
	v_mfma_f32_32x32x16_bf16 v[82:97], v[102:105], v[118:121], v[82:97]
	s_waitcnt lgkmcnt(5)
	v_mfma_f32_32x32x16_bf16 v[82:97], v[106:109], v[126:129], v[82:97]
	s_waitcnt lgkmcnt(4)
	v_mfma_f32_32x32x16_bf16 v[82:97], v[110:113], v[130:133], v[82:97]
	s_waitcnt lgkmcnt(3)
	v_mfma_f32_32x32x16_bf16 v[98:113], v[154:157], v[114:117], 0
	s_waitcnt lgkmcnt(2)
	v_mfma_f32_32x32x16_bf16 v[98:113], v[190:193], v[118:121], v[98:113]
	s_waitcnt lgkmcnt(1)
	v_mfma_f32_32x32x16_bf16 v[98:113], v[214:217], v[126:129], v[98:113]
	s_waitcnt lgkmcnt(0)
	v_mfma_f32_32x32x16_bf16 v[98:113], v[234:237], v[130:133], v[98:113]
	s_setprio 0
	s_cbranch_scc1 .LBB0_54
	v_mbcnt_lo_u32_b32 v154, -1, 0
	v_mbcnt_hi_u32_b32 v154, -1, v154
	v_lshrrev_b32_e32 v155, 5, v154
	v_and_b32_e32 v154, 31, v154
	v_lshlrev_b32_e32 v155, 2, v155
	v_sub_u32_e32 v154, v154, v155
	s_sub_u32 s78, s10, s1
	s_cmp_eq_u32 s78, 63
	s_cbranch_scc1 .Lda_mE_c2
	v_cmp_gt_i32_e64 vcc, 0, v154
	v_cmp_gt_i32_e64 s[78:79], 1, v154
	v_cmp_gt_i32_e64 s[64:65], 2, v154
	v_cndmask_b32_e64 v98, v98, v220, vcc
	v_cndmask_b32_e64 v99, v99, v220, s[78:79]
	v_cndmask_b32_e64 v100, v100, v220, s[64:65]
	v_cmp_gt_i32_e64 vcc, 3, v154
	v_cmp_gt_i32_e64 s[78:79], 8, v154
	v_cmp_gt_i32_e64 s[64:65], 9, v154
	v_cndmask_b32_e64 v101, v101, v220, vcc
	v_cndmask_b32_e64 v102, v102, v220, s[78:79]
	v_cndmask_b32_e64 v103, v103, v220, s[64:65]
	v_cmp_gt_i32_e64 vcc, 10, v154
	v_cmp_gt_i32_e64 s[78:79], 11, v154
	v_cmp_gt_i32_e64 s[64:65], 16, v154
	v_cndmask_b32_e64 v104, v104, v220, vcc
	v_cndmask_b32_e64 v105, v105, v220, s[78:79]
	v_cndmask_b32_e64 v106, v106, v220, s[64:65]
	v_cmp_gt_i32_e64 vcc, 17, v154
	v_cmp_gt_i32_e64 s[78:79], 18, v154
	v_cmp_gt_i32_e64 s[64:65], 19, v154
	v_cndmask_b32_e64 v107, v107, v220, vcc
	v_cndmask_b32_e64 v108, v108, v220, s[78:79]
	v_cndmask_b32_e64 v109, v109, v220, s[64:65]
	v_cmp_gt_i32_e64 vcc, 24, v154
	v_cmp_gt_i32_e64 s[78:79], 25, v154
	v_cmp_gt_i32_e64 s[64:65], 26, v154
	v_cndmask_b32_e64 v110, v110, v220, vcc
	v_cndmask_b32_e64 v111, v111, v220, s[78:79]
	v_cndmask_b32_e64 v112, v112, v220, s[64:65]
	v_cmp_gt_i32_e64 vcc, 27, v154
	s_nop 1
	v_cndmask_b32_e64 v113, v113, v220, vcc
	s_branch .LBB0_54
.Lda_mE_c2:
	v_cmp_gt_i32_e64 vcc, 0, v154
	v_cmp_gt_i32_e64 s[78:79], 1, v154
	v_cmp_gt_i32_e64 s[64:65], 2, v154
	v_cndmask_b32_e64 v82, v82, v220, vcc
	v_cndmask_b32_e64 v83, v83, v220, s[78:79]
	v_cndmask_b32_e64 v84, v84, v220, s[64:65]
	v_cmp_gt_i32_e64 vcc, 3, v154
	v_cmp_gt_i32_e64 s[78:79], 8, v154
	v_cmp_gt_i32_e64 s[64:65], 9, v154
	v_cndmask_b32_e64 v85, v85, v220, vcc
	v_cndmask_b32_e64 v86, v86, v220, s[78:79]
	v_cndmask_b32_e64 v87, v87, v220, s[64:65]
	v_cmp_gt_i32_e64 vcc, 10, v154
	v_cmp_gt_i32_e64 s[78:79], 11, v154
	v_cmp_gt_i32_e64 s[64:65], 16, v154
	v_cndmask_b32_e64 v88, v88, v220, vcc
	v_cndmask_b32_e64 v89, v89, v220, s[78:79]
	v_cndmask_b32_e64 v90, v90, v220, s[64:65]
	v_cmp_gt_i32_e64 vcc, 17, v154
	v_cmp_gt_i32_e64 s[78:79], 18, v154
	v_cmp_gt_i32_e64 s[64:65], 19, v154
	v_cndmask_b32_e64 v91, v91, v220, vcc
	v_cndmask_b32_e64 v92, v92, v220, s[78:79]
	v_cndmask_b32_e64 v93, v93, v220, s[64:65]
	v_cmp_gt_i32_e64 vcc, 24, v154
	v_cmp_gt_i32_e64 s[78:79], 25, v154
	v_cmp_gt_i32_e64 s[64:65], 26, v154
	v_cndmask_b32_e64 v94, v94, v220, vcc
	v_cndmask_b32_e64 v95, v95, v220, s[78:79]
	v_cndmask_b32_e64 v96, v96, v220, s[64:65]
	v_cmp_gt_i32_e64 vcc, 27, v154
	s_nop 1
	v_cndmask_b32_e64 v97, v97, v220, vcc
	v_mov_b32_e32 v98, v220
	v_mov_b32_e32 v99, v220
	v_mov_b32_e32 v100, v220
	v_mov_b32_e32 v101, v220
	v_mov_b32_e32 v102, v220
	v_mov_b32_e32 v103, v220
	v_mov_b32_e32 v104, v220
	v_mov_b32_e32 v105, v220
	v_mov_b32_e32 v106, v220
	v_mov_b32_e32 v107, v220
	v_mov_b32_e32 v108, v220
	v_mov_b32_e32 v109, v220
	v_mov_b32_e32 v110, v220
	v_mov_b32_e32 v111, v220
	v_mov_b32_e32 v112, v220
	v_mov_b32_e32 v113, v220

.LBB0_66:
	s_add_i32 s23, s4, -1
	s_and_b32 s23, s23, 1
	s_cmp_gt_u32 s22, s11
	s_cbranch_scc1 .LBB0_73
	s_mul_i32 s26, s23, 0x7400
	s_add_i32 s26, s26, 0
	s_add_i32 s30, s22, 63
	s_cmp_le_u32 s30, s1
	v_add3_u32 v206, s26, v177, v178
	ds_read_b128 v[98:101], v206
	ds_read_b128 v[102:105], v206 offset:32
	ds_read_b128 v[106:109], v206 offset:64
	ds_read_b128 v[110:113], v206 offset:96
	ds_read_b128 v[190:193], v206 offset:4608
	ds_read_b128 v[214:217], v206 offset:4640
	ds_read_b128 v[244:247], v206 offset:4672
	ds_read_b128 v[206:209], v206 offset:4704
	s_setprio 1
	s_waitcnt lgkmcnt(7)
	v_mfma_f32_32x32x16_bf16 v[82:97], v[98:101], v[126:129], 0
	s_waitcnt lgkmcnt(6)
	v_mfma_f32_32x32x16_bf16 v[82:97], v[102:105], v[130:133], v[82:97]
	s_waitcnt lgkmcnt(5)
	v_mfma_f32_32x32x16_bf16 v[82:97], v[106:109], v[134:137], v[82:97]
	s_waitcnt lgkmcnt(4)
	v_mfma_f32_32x32x16_bf16 v[82:97], v[110:113], v[138:141], v[82:97]
	s_waitcnt lgkmcnt(3)
	v_mfma_f32_32x32x16_bf16 v[98:113], v[190:193], v[126:129], 0
	s_waitcnt lgkmcnt(2)
	v_mfma_f32_32x32x16_bf16 v[98:113], v[214:217], v[130:133], v[98:113]
	s_waitcnt lgkmcnt(1)
	v_mfma_f32_32x32x16_bf16 v[98:113], v[244:247], v[134:137], v[98:113]
	s_waitcnt lgkmcnt(0)
	v_mfma_f32_32x32x16_bf16 v[98:113], v[206:209], v[138:141], v[98:113]
	s_setprio 0
	s_cbranch_scc1 .LBB0_69
	v_mbcnt_lo_u32_b32 v190, -1, 0
	v_mbcnt_hi_u32_b32 v190, -1, v190
	v_lshrrev_b32_e32 v191, 5, v190
	v_and_b32_e32 v190, 31, v190
	v_lshlrev_b32_e32 v191, 2, v191
	v_sub_u32_e32 v190, v190, v191
	s_sub_u32 s78, s30, s1
	s_cmp_eq_u32 s78, 63
	s_cbranch_scc1 .Lda_mE_c3
	v_cmp_gt_i32_e64 vcc, 0, v190
	v_cmp_gt_i32_e64 s[78:79], 1, v190
	v_cmp_gt_i32_e64 s[30:31], 2, v190
	v_cndmask_b32_e64 v98, v98, v220, vcc
	v_cndmask_b32_e64 v99, v99, v220, s[78:79]
	v_cndmask_b32_e64 v100, v100, v220, s[30:31]
	v_cmp_gt_i32_e64 vcc, 3, v190
	v_cmp_gt_i32_e64 s[78:79], 8, v190
	v_cmp_gt_i32_e64 s[30:31], 9, v190
	v_cndmask_b32_e64 v101, v101, v220, vcc
	v_cndmask_b32_e64 v102, v102, v220, s[78:79]
	v_cndmask_b32_e64 v103, v103, v220, s[30:31]
	v_cmp_gt_i32_e64 vcc, 10, v190
	v_cmp_gt_i32_e64 s[78:79], 11, v190
	v_cmp_gt_i32_e64 s[30:31], 16, v190
	v_cndmask_b32_e64 v104, v104, v220, vcc
	v_cndmask_b32_e64 v105, v105, v220, s[78:79]
	v_cndmask_b32_e64 v106, v106, v220, s[30:31]
	v_cmp_gt_i32_e64 vcc, 17, v190
	v_cmp_gt_i32_e64 s[78:79], 18, v190
	v_cmp_gt_i32_e64 s[30:31], 19, v190
	v_cndmask_b32_e64 v107, v107, v220, vcc
	v_cndmask_b32_e64 v108, v108, v220, s[78:79]
	v_cndmask_b32_e64 v109, v109, v220, s[30:31]
	v_cmp_gt_i32_e64 vcc, 24, v190
	v_cmp_gt_i32_e64 s[78:79], 25, v190
	v_cmp_gt_i32_e64 s[30:31], 26, v190
	v_cndmask_b32_e64 v110, v110, v220, vcc
	v_cndmask_b32_e64 v111, v111, v220, s[78:79]
	v_cndmask_b32_e64 v112, v112, v220, s[30:31]
	v_cmp_gt_i32_e64 vcc, 27, v190
	s_nop 1
	v_cndmask_b32_e64 v113, v113, v220, vcc
	s_branch .LBB0_69
.Lda_mE_c3:
	v_cmp_gt_i32_e64 vcc, 0, v190
	v_cmp_gt_i32_e64 s[78:79], 1, v190
	v_cmp_gt_i32_e64 s[30:31], 2, v190
	v_cndmask_b32_e64 v82, v82, v220, vcc
	v_cndmask_b32_e64 v83, v83, v220, s[78:79]
	v_cndmask_b32_e64 v84, v84, v220, s[30:31]
	v_cmp_gt_i32_e64 vcc, 3, v190
	v_cmp_gt_i32_e64 s[78:79], 8, v190
	v_cmp_gt_i32_e64 s[30:31], 9, v190
	v_cndmask_b32_e64 v85, v85, v220, vcc
	v_cndmask_b32_e64 v86, v86, v220, s[78:79]
	v_cndmask_b32_e64 v87, v87, v220, s[30:31]
	v_cmp_gt_i32_e64 vcc, 10, v190
	v_cmp_gt_i32_e64 s[78:79], 11, v190
	v_cmp_gt_i32_e64 s[30:31], 16, v190
	v_cndmask_b32_e64 v88, v88, v220, vcc
	v_cndmask_b32_e64 v89, v89, v220, s[78:79]
	v_cndmask_b32_e64 v90, v90, v220, s[30:31]
	v_cmp_gt_i32_e64 vcc, 17, v190
	v_cmp_gt_i32_e64 s[78:79], 18, v190
	v_cmp_gt_i32_e64 s[30:31], 19, v190
	v_cndmask_b32_e64 v91, v91, v220, vcc
	v_cndmask_b32_e64 v92, v92, v220, s[78:79]
	v_cndmask_b32_e64 v93, v93, v220, s[30:31]
	v_cmp_gt_i32_e64 vcc, 24, v190
	v_cmp_gt_i32_e64 s[78:79], 25, v190
	v_cmp_gt_i32_e64 s[30:31], 26, v190
	v_cndmask_b32_e64 v94, v94, v220, vcc
	v_cndmask_b32_e64 v95, v95, v220, s[78:79]
	v_cndmask_b32_e64 v96, v96, v220, s[30:31]
	v_cmp_gt_i32_e64 vcc, 27, v190
	s_nop 1
	v_cndmask_b32_e64 v97, v97, v220, vcc
	v_mov_b32_e32 v98, v220
	v_mov_b32_e32 v99, v220
	v_mov_b32_e32 v100, v220
	v_mov_b32_e32 v101, v220
	v_mov_b32_e32 v102, v220
	v_mov_b32_e32 v103, v220
	v_mov_b32_e32 v104, v220
	v_mov_b32_e32 v105, v220
	v_mov_b32_e32 v106, v220
	v_mov_b32_e32 v107, v220
	v_mov_b32_e32 v108, v220
	v_mov_b32_e32 v109, v220
	v_mov_b32_e32 v110, v220
	v_mov_b32_e32 v111, v220
	v_mov_b32_e32 v112, v220
	v_mov_b32_e32 v113, v220

.LBB0_81:
	s_add_i32 s23, s22, -1
	s_and_b32 s23, s23, 1
	s_cmp_gt_u32 s4, s11
	s_cbranch_scc1 .LBB0_88
	s_mul_i32 s26, s23, 0x7400
	s_add_i32 s26, s26, 0
	s_add_i32 s30, s4, 63
	s_cmp_le_u32 s30, s1
	v_add3_u32 v152, s26, v177, v178
	ds_read_b128 v[98:101], v152
	ds_read_b128 v[102:105], v152 offset:32
	ds_read_b128 v[106:109], v152 offset:64
	ds_read_b128 v[110:113], v152 offset:96
	ds_read_b128 v[154:157], v152 offset:4608
	ds_read_b128 v[162:165], v152 offset:4640
	ds_read_b128 v[190:193], v152 offset:4672
	ds_read_b128 v[206:209], v152 offset:4704
	s_setprio 1
	s_waitcnt lgkmcnt(7)
	v_mfma_f32_32x32x16_bf16 v[82:97], v[98:101], v[118:121], 0
	s_waitcnt lgkmcnt(6)
	v_mfma_f32_32x32x16_bf16 v[82:97], v[102:105], v[122:125], v[82:97]
	s_waitcnt lgkmcnt(5)
	v_mfma_f32_32x32x16_bf16 v[82:97], v[106:109], v[126:129], v[82:97]
	s_waitcnt lgkmcnt(4)
	v_mfma_f32_32x32x16_bf16 v[82:97], v[110:113], v[134:137], v[82:97]
	s_waitcnt lgkmcnt(3)
	v_mfma_f32_32x32x16_bf16 v[98:113], v[154:157], v[118:121], 0
	s_waitcnt lgkmcnt(2)
	v_mfma_f32_32x32x16_bf16 v[98:113], v[162:165], v[122:125], v[98:113]
	s_waitcnt lgkmcnt(1)
	v_mfma_f32_32x32x16_bf16 v[98:113], v[190:193], v[126:129], v[98:113]
	s_waitcnt lgkmcnt(0)
	v_mfma_f32_32x32x16_bf16 v[98:113], v[206:209], v[134:137], v[98:113]
	s_setprio 0
	s_cbranch_scc1 .LBB0_84
	v_mbcnt_lo_u32_b32 v154, -1, 0
	v_mbcnt_hi_u32_b32 v154, -1, v154
	v_lshrrev_b32_e32 v155, 5, v154
	v_and_b32_e32 v154, 31, v154
	v_lshlrev_b32_e32 v155, 2, v155
	v_sub_u32_e32 v154, v154, v155
	s_sub_u32 s78, s30, s1
	s_cmp_eq_u32 s78, 63
	s_cbranch_scc1 .Lda_mE_c4
	v_cmp_gt_i32_e64 vcc, 0, v154
	v_cmp_gt_i32_e64 s[78:79], 1, v154
	v_cmp_gt_i32_e64 s[30:31], 2, v154
	v_cndmask_b32_e64 v98, v98, v220, vcc
	v_cndmask_b32_e64 v99, v99, v220, s[78:79]
	v_cndmask_b32_e64 v100, v100, v220, s[30:31]
	v_cmp_gt_i32_e64 vcc, 3, v154
	v_cmp_gt_i32_e64 s[78:79], 8, v154
	v_cmp_gt_i32_e64 s[30:31], 9, v154
	v_cndmask_b32_e64 v101, v101, v220, vcc
	v_cndmask_b32_e64 v102, v102, v220, s[78:79]
	v_cndmask_b32_e64 v103, v103, v220, s[30:31]
	v_cmp_gt_i32_e64 vcc, 10, v154
	v_cmp_gt_i32_e64 s[78:79], 11, v154
	v_cmp_gt_i32_e64 s[30:31], 16, v154
	v_cndmask_b32_e64 v104, v104, v220, vcc
	v_cndmask_b32_e64 v105, v105, v220, s[78:79]
	v_cndmask_b32_e64 v106, v106, v220, s[30:31]
	v_cmp_gt_i32_e64 vcc, 17, v154
	v_cmp_gt_i32_e64 s[78:79], 18, v154
	v_cmp_gt_i32_e64 s[30:31], 19, v154
	v_cndmask_b32_e64 v107, v107, v220, vcc
	v_cndmask_b32_e64 v108, v108, v220, s[78:79]
	v_cndmask_b32_e64 v109, v109, v220, s[30:31]
	v_cmp_gt_i32_e64 vcc, 24, v154
	v_cmp_gt_i32_e64 s[78:79], 25, v154
	v_cmp_gt_i32_e64 s[30:31], 26, v154
	v_cndmask_b32_e64 v110, v110, v220, vcc
	v_cndmask_b32_e64 v111, v111, v220, s[78:79]
	v_cndmask_b32_e64 v112, v112, v220, s[30:31]
	v_cmp_gt_i32_e64 vcc, 27, v154
	s_nop 1
	v_cndmask_b32_e64 v113, v113, v220, vcc
	s_branch .LBB0_84
.Lda_mE_c4:
	v_cmp_gt_i32_e64 vcc, 0, v154
	v_cmp_gt_i32_e64 s[78:79], 1, v154
	v_cmp_gt_i32_e64 s[30:31], 2, v154
	v_cndmask_b32_e64 v82, v82, v220, vcc
	v_cndmask_b32_e64 v83, v83, v220, s[78:79]
	v_cndmask_b32_e64 v84, v84, v220, s[30:31]
	v_cmp_gt_i32_e64 vcc, 3, v154
	v_cmp_gt_i32_e64 s[78:79], 8, v154
	v_cmp_gt_i32_e64 s[30:31], 9, v154
	v_cndmask_b32_e64 v85, v85, v220, vcc
	v_cndmask_b32_e64 v86, v86, v220, s[78:79]
	v_cndmask_b32_e64 v87, v87, v220, s[30:31]
	v_cmp_gt_i32_e64 vcc, 10, v154
	v_cmp_gt_i32_e64 s[78:79], 11, v154
	v_cmp_gt_i32_e64 s[30:31], 16, v154
	v_cndmask_b32_e64 v88, v88, v220, vcc
	v_cndmask_b32_e64 v89, v89, v220, s[78:79]
	v_cndmask_b32_e64 v90, v90, v220, s[30:31]
	v_cmp_gt_i32_e64 vcc, 17, v154
	v_cmp_gt_i32_e64 s[78:79], 18, v154
	v_cmp_gt_i32_e64 s[30:31], 19, v154
	v_cndmask_b32_e64 v91, v91, v220, vcc
	v_cndmask_b32_e64 v92, v92, v220, s[78:79]
	v_cndmask_b32_e64 v93, v93, v220, s[30:31]
	v_cmp_gt_i32_e64 vcc, 24, v154
	v_cmp_gt_i32_e64 s[78:79], 25, v154
	v_cmp_gt_i32_e64 s[30:31], 26, v154
	v_cndmask_b32_e64 v94, v94, v220, vcc
	v_cndmask_b32_e64 v95, v95, v220, s[78:79]
	v_cndmask_b32_e64 v96, v96, v220, s[30:31]
	v_cmp_gt_i32_e64 vcc, 27, v154
	s_nop 1
	v_cndmask_b32_e64 v97, v97, v220, vcc
	v_mov_b32_e32 v98, v220
	v_mov_b32_e32 v99, v220
	v_mov_b32_e32 v100, v220
	v_mov_b32_e32 v101, v220
	v_mov_b32_e32 v102, v220
	v_mov_b32_e32 v103, v220
	v_mov_b32_e32 v104, v220
	v_mov_b32_e32 v105, v220
	v_mov_b32_e32 v106, v220
	v_mov_b32_e32 v107, v220
	v_mov_b32_e32 v108, v220
	v_mov_b32_e32 v109, v220
	v_mov_b32_e32 v110, v220
	v_mov_b32_e32 v111, v220
	v_mov_b32_e32 v112, v220
	v_mov_b32_e32 v113, v220
